# scan step5: 16-lane bpermute butterflies replaced by DPP adds (bit-identical sums)
# speedup vs baseline: 1.0099x; 1.0099x over previous
.LBB0_380:
	s_or_b64 exec, exec, s[94:95]
	s_add_i32 s14, s15, 1
	s_cmp_lt_u32 s14, s0
	s_cselect_b32 s15, s14, s15
	s_lshl_b32 s16, s15, 6
	v_add_u32_e32 v2, s13, v231
	s_add_i32 s16, s16, s97
	v_ashrrev_i32_e32 v3, 31, v2
	s_cmp_eq_u32 s15, 0
	v_lshlrev_b64 v[2:3], 12, v[2:3]
	s_cselect_b32 s15, 0, 0x1000
	v_lshl_add_u64 v[190:191], v[164:165], 0, v[2:3]
	v_add_u32_e32 v2, s16, v1
	v_mov_b32_e32 v84, s15
	v_ashrrev_i32_e32 v3, 31, v2
	v_cndmask_b32_e64 v86, v84, v195, s[6:7]
	v_lshlrev_b64 v[2:3], 13, v[2:3]
	v_mul_u32_u24_e32 v84, 3, v86
	v_lshl_add_u64 v[2:3], v[176:177], 0, v[2:3]
	v_lshlrev_b32_e32 v84, 1, v84
	v_sub_co_u32_e32 v84, vcc, v2, v84
	global_load_dwordx4 v[76:79], v[190:191], off
	global_load_dwordx4 v[80:83], v[190:191], off offset:128
	global_load_dwordx4 v[72:75], v[190:191], off offset:256
	global_load_dwordx4 v[68:71], v[190:191], off offset:384
	s_waitcnt lgkmcnt(0)
	s_barrier
	v_subbrev_co_u32_e32 v85, vcc, 0, v3, vcc
	global_load_dword v250, v[84:85], off
	v_lshlrev_b32_e32 v84, 2, v86
	v_sub_co_u32_e32 v84, vcc, v2, v84
	v_lshlrev_b32_e32 v87, 1, v86
	s_nop 0
	v_subbrev_co_u32_e32 v85, vcc, 0, v3, vcc
	global_load_dword v251, v[84:85], off
	v_sub_co_u32_e32 v84, vcc, v2, v87
	s_movk_i32 s15, 0x2000
	s_nop 0
	v_subbrev_co_u32_e32 v85, vcc, 0, v3, vcc
	global_load_dword v252, v[84:85], off
	global_load_dword v249, v[2:3], off
	v_add_co_u32_e32 v84, vcc, s15, v2
	s_movk_i32 s15, 0x4000
	s_nop 0
	v_addc_co_u32_e32 v85, vcc, 0, v3, vcc
	global_load_dword v248, v[84:85], off
	v_add_co_u32_e32 v84, vcc, s15, v2
	s_movk_i32 s15, 0x6000
	s_nop 0
	v_addc_co_u32_e32 v85, vcc, 0, v3, vcc
	global_load_dword v247, v[84:85], off
	v_add_co_u32_e32 v84, vcc, s15, v2
	s_mov_b32 s15, 0x8000
	s_nop 0
	v_addc_co_u32_e32 v85, vcc, 0, v3, vcc
	global_load_dword v246, v[84:85], off
	v_add_co_u32_e32 v84, vcc, s15, v2
	s_mov_b32 s15, 0xa000
	s_nop 0
	v_addc_co_u32_e32 v85, vcc, 0, v3, vcc
	global_load_dword v245, v[84:85], off
	v_add_co_u32_e32 v84, vcc, s15, v2
	s_mov_b32 s15, 0xc000
	s_nop 0
	v_addc_co_u32_e32 v85, vcc, 0, v3, vcc
	global_load_dword v244, v[84:85], off
	v_add_co_u32_e32 v84, vcc, s15, v2
	s_mov_b32 s15, 0xe000
	s_nop 0
	v_addc_co_u32_e32 v85, vcc, 0, v3, vcc
	global_load_dword v243, v[84:85], off
	v_add_co_u32_e32 v84, vcc, s15, v2
	s_mov_b32 s15, 0x10000
	s_nop 0
	v_addc_co_u32_e32 v85, vcc, 0, v3, vcc
	global_load_dword v242, v[84:85], off
	v_add_co_u32_e32 v84, vcc, s15, v2
	s_mov_b32 s15, 0x12000
	s_nop 0
	v_addc_co_u32_e32 v85, vcc, 0, v3, vcc
	global_load_dword v241, v[84:85], off
	v_add_co_u32_e32 v84, vcc, s15, v2
	s_mov_b32 s15, 0x14000
	s_nop 0
	v_addc_co_u32_e32 v85, vcc, 0, v3, vcc
	global_load_dword v240, v[84:85], off
	v_add_co_u32_e32 v84, vcc, s15, v2
	s_mov_b32 s15, 0x16000
	s_nop 0
	v_addc_co_u32_e32 v85, vcc, 0, v3, vcc
	global_load_dword v239, v[84:85], off
	v_add_co_u32_e32 v84, vcc, s15, v2
	s_mov_b32 s15, 0x18000
	s_nop 0
	v_addc_co_u32_e32 v85, vcc, 0, v3, vcc
	global_load_dword v238, v[84:85], off
	v_add_co_u32_e32 v84, vcc, s15, v2
	s_mov_b32 s15, 0x1a000
	s_nop 0
	v_addc_co_u32_e32 v85, vcc, 0, v3, vcc
	v_add_co_u32_e32 v2, vcc, s15, v2
	global_load_dword v237, v[84:85], off
	s_nop 0
	v_addc_co_u32_e32 v3, vcc, 0, v3, vcc
	global_load_dword v236, v[2:3], off
	v_add_u32_e32 v2, s16, v159
	v_ashrrev_i32_e32 v3, 31, v2
	v_lshlrev_b64 v[2:3], 7, v[2:3]
	v_lshl_add_u64 v[2:3], s[90:91], 0, v[2:3]
	global_load_dword v153, v[2:3], off
	ds_read_b128 v[84:87], v180
	ds_read_b128 v[88:91], v181 offset:17408
	ds_read_b128 v[92:95], v181 offset:21760
	v_add_u32_e32 v192, v178, v228
	s_waitcnt lgkmcnt(1)
	v_mfma_f32_16x16x32_bf16 v[88:91], v[84:87], v[88:91], 0
	s_waitcnt lgkmcnt(0)
	v_mfma_f32_16x16x32_bf16 v[84:87], v[84:87], v[92:95], 0
	ds_read_b128 v[92:95], v180 offset:64
	ds_read_b128 v[96:99], v181 offset:17472
	ds_read_b128 v[100:103], v181 offset:21824
	s_waitcnt lgkmcnt(1)
	v_mfma_f32_16x16x32_bf16 v[88:91], v[92:95], v[96:99], v[88:91]
	s_waitcnt lgkmcnt(0)
	v_mfma_f32_16x16x32_bf16 v[84:87], v[92:95], v[100:103], v[84:87]
	ds_read_b128 v[92:95], v180 offset:128
	ds_read_b128 v[96:99], v181 offset:17536
	ds_read_b128 v[100:103], v181 offset:21888
	s_waitcnt lgkmcnt(1)
	v_mfma_f32_16x16x32_bf16 v[88:91], v[92:95], v[96:99], v[88:91]
	s_waitcnt lgkmcnt(0)
	v_mfma_f32_16x16x32_bf16 v[84:87], v[92:95], v[100:103], v[84:87]
	ds_read_b128 v[92:95], v180 offset:192
	ds_read_b128 v[96:99], v181 offset:17600
	ds_read_b128 v[100:103], v181 offset:21952
	s_waitcnt lgkmcnt(1)
	v_mfma_f32_16x16x32_bf16 v[88:91], v[92:95], v[96:99], v[88:91]
	s_waitcnt lgkmcnt(0)
	v_mfma_f32_16x16x32_bf16 v[84:87], v[92:95], v[100:103], v[84:87]
	s_nop 7
	ds_write2_b32 v202, v88, v84 offset1:16
	ds_write2_b32 v202, v89, v85 offset0:68 offset1:84
	ds_write2_b32 v202, v90, v86 offset0:136 offset1:152
	ds_write2_b32 v202, v91, v87 offset0:204 offset1:220
	v_cvt_pk_bf16_f32 v84, v4, v5
	v_cvt_pk_bf16_f32 v85, v6, v7
	v_cvt_pk_bf16_f32 v86, v12, v13
	v_cvt_pk_bf16_f32 v87, v14, v15
	v_cvt_pk_bf16_f32 v88, v8, v9
	v_cvt_pk_bf16_f32 v89, v10, v11
	v_cvt_pk_bf16_f32 v90, v16, v17
	v_cvt_pk_bf16_f32 v91, v18, v19
	ds_read2_b64 v[92:95], v224 offset1:4
	ds_read2_b64 v[100:103], v225 offset1:4
	ds_read2_b64 v[108:111], v226 offset1:4
	ds_read2_b64 v[116:119], v227 offset1:4
	s_waitcnt lgkmcnt(3)
	v_mfma_f32_16x16x32_bf16 v[96:99], v[92:95], v[84:87], 0
	v_mfma_f32_16x16x32_bf16 v[92:95], v[92:95], v[88:91], 0
	s_waitcnt lgkmcnt(2)
	v_mfma_f32_16x16x32_bf16 v[104:107], v[100:103], v[84:87], 0
	v_mfma_f32_16x16x32_bf16 v[100:103], v[100:103], v[88:91], 0
	s_waitcnt lgkmcnt(1)
	v_mfma_f32_16x16x32_bf16 v[112:115], v[108:111], v[84:87], 0
	v_mfma_f32_16x16x32_bf16 v[108:111], v[108:111], v[88:91], 0
	s_waitcnt lgkmcnt(0)
	v_mfma_f32_16x16x32_bf16 v[84:87], v[116:119], v[84:87], 0
	v_mfma_f32_16x16x32_bf16 v[88:91], v[116:119], v[88:91], 0
	v_cvt_pk_bf16_f32 v116, v20, v21
	v_cvt_pk_bf16_f32 v117, v22, v23
	v_cvt_pk_bf16_f32 v118, v28, v29
	v_cvt_pk_bf16_f32 v119, v30, v31
	v_cvt_pk_bf16_f32 v120, v24, v25
	v_cvt_pk_bf16_f32 v121, v26, v27
	v_cvt_pk_bf16_f32 v122, v32, v33
	v_cvt_pk_bf16_f32 v123, v34, v35
	ds_read2_b64 v[124:127], v224 offset0:8 offset1:12
	s_waitcnt lgkmcnt(0)
	v_mfma_f32_16x16x32_bf16 v[96:99], v[124:127], v[116:119], v[96:99]
	v_mfma_f32_16x16x32_bf16 v[92:95], v[124:127], v[120:123], v[92:95]
	ds_read2_b64 v[124:127], v225 offset0:8 offset1:12
	s_waitcnt lgkmcnt(0)
	v_mfma_f32_16x16x32_bf16 v[104:107], v[124:127], v[116:119], v[104:107]
	v_mfma_f32_16x16x32_bf16 v[100:103], v[124:127], v[120:123], v[100:103]
	ds_read2_b64 v[124:127], v226 offset0:8 offset1:12
	s_waitcnt lgkmcnt(0)
	v_mfma_f32_16x16x32_bf16 v[112:115], v[124:127], v[116:119], v[112:115]
	v_mfma_f32_16x16x32_bf16 v[108:111], v[124:127], v[120:123], v[108:111]
	ds_read2_b64 v[124:127], v227 offset0:8 offset1:12
	s_waitcnt lgkmcnt(0)
	v_mfma_f32_16x16x32_bf16 v[84:87], v[124:127], v[116:119], v[84:87]
	v_cvt_pk_bf16_f32 v116, v36, v37
	v_cvt_pk_bf16_f32 v117, v38, v39
	v_cvt_pk_bf16_f32 v118, v44, v45
	v_mfma_f32_16x16x32_bf16 v[88:91], v[124:127], v[120:123], v[88:91]
	v_cvt_pk_bf16_f32 v119, v46, v47
	v_cvt_pk_bf16_f32 v120, v40, v41
	v_cvt_pk_bf16_f32 v121, v42, v43
	v_cvt_pk_bf16_f32 v122, v48, v49
	v_cvt_pk_bf16_f32 v123, v50, v51
	ds_read2_b64 v[124:127], v224 offset0:16 offset1:20
	s_waitcnt lgkmcnt(0)
	v_mfma_f32_16x16x32_bf16 v[96:99], v[124:127], v[116:119], v[96:99]
	v_mfma_f32_16x16x32_bf16 v[92:95], v[124:127], v[120:123], v[92:95]
	ds_read2_b64 v[124:127], v225 offset0:16 offset1:20
	s_waitcnt lgkmcnt(0)
	v_mfma_f32_16x16x32_bf16 v[104:107], v[124:127], v[116:119], v[104:107]
	v_mfma_f32_16x16x32_bf16 v[100:103], v[124:127], v[120:123], v[100:103]
	ds_read2_b64 v[124:127], v226 offset0:16 offset1:20
	s_waitcnt lgkmcnt(0)
	v_mfma_f32_16x16x32_bf16 v[112:115], v[124:127], v[116:119], v[112:115]
	v_mfma_f32_16x16x32_bf16 v[108:111], v[124:127], v[120:123], v[108:111]
	ds_read2_b64 v[124:127], v227 offset0:16 offset1:20
	s_waitcnt lgkmcnt(0)
	v_mfma_f32_16x16x32_bf16 v[84:87], v[124:127], v[116:119], v[84:87]
	v_mfma_f32_16x16x32_bf16 v[116:119], v[124:127], v[120:123], v[88:91]
	v_cvt_pk_bf16_f32 v88, v52, v53
	v_cvt_pk_bf16_f32 v89, v54, v55
	v_cvt_pk_bf16_f32 v90, v60, v61
	v_cvt_pk_bf16_f32 v91, v62, v63
	v_cvt_pk_bf16_f32 v120, v56, v57
	v_cvt_pk_bf16_f32 v121, v58, v59
	v_cvt_pk_bf16_f32 v122, v64, v65
	v_cvt_pk_bf16_f32 v123, v66, v67
	ds_read2_b64 v[124:127], v224 offset0:24 offset1:28
	s_waitcnt lgkmcnt(0)
	v_mfma_f32_16x16x32_bf16 v[128:131], v[124:127], v[88:91], v[96:99]
	v_mfma_f32_16x16x32_bf16 v[124:127], v[124:127], v[120:123], v[92:95]
	s_nop 2
	ds_read2_b64 v[92:95], v225 offset0:24 offset1:28
	s_waitcnt lgkmcnt(0)
	v_mfma_f32_16x16x32_bf16 v[104:107], v[92:95], v[88:91], v[104:107]
	v_mfma_f32_16x16x32_bf16 v[132:135], v[92:95], v[120:123], v[100:103]
	ds_read2_b64 v[92:95], v226 offset0:24 offset1:28
	s_waitcnt lgkmcnt(0)
	v_mfma_f32_16x16x32_bf16 v[100:103], v[92:95], v[88:91], v[112:115]
	v_mfma_f32_16x16x32_bf16 v[96:99], v[92:95], v[120:123], v[108:111]
	ds_read2_b64 v[92:95], v227 offset0:24 offset1:28
	s_waitcnt lgkmcnt(0)
	v_mfma_f32_16x16x32_bf16 v[88:91], v[92:95], v[88:91], v[84:87]
	v_mfma_f32_16x16x32_bf16 v[92:95], v[92:95], v[120:123], v[116:119]
	v_add_u32_e32 v120, s33, v156
	s_nop 0
	ds_read_b128 v[84:87], v120
	s_waitcnt lgkmcnt(0)
	v_mul_f32_e32 v2, 0x3fb8aa3b, v84
	v_mul_f32_e32 v84, 0x3fb8aa3b, v86
	v_exp_f32_e32 v108, v84
	v_mul_f32_e32 v84, 0x3fb8aa3b, v87
	v_exp_f32_e32 v109, v84
	v_mul_f32_e32 v3, 0x3fb8aa3b, v85
	v_exp_f32_e32 v2, v2
	v_exp_f32_e32 v3, v3
	v_pk_mul_f32 v[86:87], v[130:131], v[108:109]
	v_pk_mul_f32 v[118:119], v[126:127], v[108:109]
	ds_read_b128 v[108:111], v120 offset:64
	v_pk_mul_f32 v[84:85], v[128:129], v[2:3]
	v_pk_mul_f32 v[116:117], v[124:125], v[2:3]
	s_waitcnt lgkmcnt(0)
	v_mul_f32_e32 v2, 0x3fb8aa3b, v108
	v_mul_f32_e32 v108, 0x3fb8aa3b, v110
	v_mul_f32_e32 v3, 0x3fb8aa3b, v109
	v_exp_f32_e32 v112, v108
	v_mul_f32_e32 v108, 0x3fb8aa3b, v111
	v_exp_f32_e32 v2, v2
	v_exp_f32_e32 v3, v3
	v_exp_f32_e32 v113, v108
	v_pk_mul_f32 v[108:109], v[104:105], v[2:3]
	v_pk_mul_f32 v[110:111], v[106:107], v[112:113]
	ds_read_b128 v[104:107], v120 offset:128
	v_pk_mul_f32 v[114:115], v[134:135], v[112:113]
	v_pk_mul_f32 v[112:113], v[132:133], v[2:3]
	s_waitcnt lgkmcnt(0)
	v_mul_f32_e32 v2, 0x3fb8aa3b, v104
	v_mul_f32_e32 v3, 0x3fb8aa3b, v105
	v_mul_f32_e32 v104, 0x3fb8aa3b, v106
	v_mul_f32_e32 v105, 0x3fb8aa3b, v107
	v_exp_f32_e32 v2, v2
	v_exp_f32_e32 v3, v3
	v_exp_f32_e32 v104, v104
	v_exp_f32_e32 v105, v105
	v_pk_mul_f32 v[100:101], v[100:101], v[2:3]
	v_pk_mul_f32 v[102:103], v[102:103], v[104:105]
	v_pk_mul_f32 v[106:107], v[98:99], v[104:105]
	v_pk_mul_f32 v[104:105], v[96:97], v[2:3]
	ds_read_b128 v[96:99], v120 offset:192
	s_waitcnt vmcnt(21)
	ds_write_b128 v230, v[76:79]
	s_waitcnt vmcnt(20)
	ds_write_b128 v230, v[80:83] offset:128
	s_waitcnt vmcnt(19)
	ds_write_b128 v230, v[72:75] offset:256
	s_waitcnt vmcnt(18)
	ds_write_b128 v230, v[68:71] offset:384
	s_waitcnt lgkmcnt(0)
	s_barrier
	s_waitcnt lgkmcnt(4)
	v_mul_f32_e32 v2, 0x3fb8aa3b, v96
	v_mul_f32_e32 v3, 0x3fb8aa3b, v97
	v_mul_f32_e32 v96, 0x3fb8aa3b, v98
	v_mul_f32_e32 v97, 0x3fb8aa3b, v99
	v_exp_f32_e32 v2, v2
	v_exp_f32_e32 v3, v3
	v_exp_f32_e32 v96, v96
	v_exp_f32_e32 v97, v97
	v_pk_mul_f32 v[88:89], v[88:89], v[2:3]
	v_pk_mul_f32 v[90:91], v[90:91], v[96:97]
	v_pk_mul_f32 v[98:99], v[94:95], v[96:97]
	v_pk_mul_f32 v[96:97], v[92:93], v[2:3]
	v_mov_b32_e32 v2, s33
	ds_read_b32 v253, v2 offset:252
	ds_read_b128 v[148:151], v209
	ds_read_b128 v[140:143], v209 offset:16
	ds_read_b128 v[144:147], v201
	ds_read_b128 v[124:127], v201 offset:16
	s_waitcnt lgkmcnt(4)
	v_mul_f32_e32 v2, 0x3fb8aa3b, v253
	v_exp_f32_e32 v2, v2
	s_nop 0
	v_pk_mul_f32 v[6:7], v[6:7], v[2:3] op_sel_hi:[1,0]
	v_pk_mul_f32 v[4:5], v[4:5], v[2:3] op_sel_hi:[1,0]
	v_pk_mul_f32 v[74:75], v[10:11], v[2:3] op_sel_hi:[1,0]
	v_pk_mul_f32 v[72:73], v[8:9], v[2:3] op_sel_hi:[1,0]
	v_pk_mul_f32 v[10:11], v[14:15], v[2:3] op_sel_hi:[1,0]
	v_pk_mul_f32 v[8:9], v[12:13], v[2:3] op_sel_hi:[1,0]
	v_pk_mul_f32 v[18:19], v[18:19], v[2:3] op_sel_hi:[1,0]
	v_pk_mul_f32 v[16:17], v[16:17], v[2:3] op_sel_hi:[1,0]
	v_pk_mul_f32 v[14:15], v[22:23], v[2:3] op_sel_hi:[1,0]
	v_pk_mul_f32 v[12:13], v[20:21], v[2:3] op_sel_hi:[1,0]
	v_pk_mul_f32 v[26:27], v[26:27], v[2:3] op_sel_hi:[1,0]
	v_pk_mul_f32 v[24:25], v[24:25], v[2:3] op_sel_hi:[1,0]
	v_pk_mul_f32 v[22:23], v[30:31], v[2:3] op_sel_hi:[1,0]
	v_pk_mul_f32 v[20:21], v[28:29], v[2:3] op_sel_hi:[1,0]
	v_pk_mul_f32 v[34:35], v[34:35], v[2:3] op_sel_hi:[1,0]
	v_pk_mul_f32 v[32:33], v[32:33], v[2:3] op_sel_hi:[1,0]
	v_pk_mul_f32 v[30:31], v[38:39], v[2:3] op_sel_hi:[1,0]
	v_pk_mul_f32 v[28:29], v[36:37], v[2:3] op_sel_hi:[1,0]
	v_pk_mul_f32 v[42:43], v[42:43], v[2:3] op_sel_hi:[1,0]
	v_pk_mul_f32 v[40:41], v[40:41], v[2:3] op_sel_hi:[1,0]
	v_pk_mul_f32 v[38:39], v[46:47], v[2:3] op_sel_hi:[1,0]
	v_pk_mul_f32 v[36:37], v[44:45], v[2:3] op_sel_hi:[1,0]
	v_pk_mul_f32 v[50:51], v[50:51], v[2:3] op_sel_hi:[1,0]
	v_pk_mul_f32 v[48:49], v[48:49], v[2:3] op_sel_hi:[1,0]
	v_pk_mul_f32 v[46:47], v[54:55], v[2:3] op_sel_hi:[1,0]
	v_pk_mul_f32 v[44:45], v[52:53], v[2:3] op_sel_hi:[1,0]
	v_pk_mul_f32 v[58:59], v[58:59], v[2:3] op_sel_hi:[1,0]
	v_pk_mul_f32 v[56:57], v[56:57], v[2:3] op_sel_hi:[1,0]
	v_pk_mul_f32 v[54:55], v[62:63], v[2:3] op_sel_hi:[1,0]
	v_pk_mul_f32 v[52:53], v[60:61], v[2:3] op_sel_hi:[1,0]
	v_pk_mul_f32 v[62:63], v[66:67], v[2:3] op_sel_hi:[1,0]
	v_pk_mul_f32 v[60:61], v[64:65], v[2:3] op_sel_hi:[1,0]
	ds_read_b128 v[120:123], v192 offset:53248
	ds_read_b128 v[64:67], v192 offset:55552
	ds_read_b32 v2, v229
	ds_read_b128 v[68:71], v232
	ds_read_b128 v[76:79], v232 offset:16
	s_waitcnt lgkmcnt(2)
	v_sub_f32_e32 v3, v2, v148
	v_mul_f32_e32 v3, 0x3fb8aa3b, v3
	v_exp_f32_e32 v3, v3
	s_waitcnt lgkmcnt(1)
	v_mul_f32_e32 v3, v68, v3
	v_sub_f32_e32 v68, v2, v149
	v_mul_f32_e32 v68, 0x3fb8aa3b, v68
	v_exp_f32_e32 v68, v68
	v_mul_f32_e32 v3, v144, v3
	v_cndmask_b32_e64 v3, v3, 0, s[24:25]
	v_mul_f32_e32 v68, v69, v68
	v_sub_f32_e32 v69, v2, v150
	v_mul_f32_e32 v69, 0x3fb8aa3b, v69
	v_exp_f32_e32 v69, v69
	v_mul_f32_e32 v68, v145, v68
	v_cndmask_b32_e64 v68, 0, v68, s[26:27]
	v_cvt_pk_bf16_f32 v68, v3, v68
	v_mul_f32_e32 v69, v70, v69
	v_sub_f32_e32 v70, v2, v151
	v_mul_f32_e32 v70, 0x3fb8aa3b, v70
	v_exp_f32_e32 v70, v70
	v_mul_f32_e32 v69, v146, v69
	v_cndmask_b32_e64 v69, v69, 0, s[28:29]
	v_mul_f32_e32 v70, v71, v70
	v_sub_f32_e32 v71, v2, v140
	v_mul_f32_e32 v71, 0x3fb8aa3b, v71
	v_exp_f32_e32 v71, v71
	v_mul_f32_e32 v70, v147, v70
	v_cndmask_b32_e64 v70, v70, 0, s[30:31]
	v_cvt_pk_bf16_f32 v69, v69, v70
	s_waitcnt lgkmcnt(0)
	v_mul_f32_e32 v71, v76, v71
	v_sub_f32_e32 v76, v2, v141
	v_mul_f32_e32 v76, 0x3fb8aa3b, v76
	v_exp_f32_e32 v76, v76
	v_mul_f32_e32 v71, v124, v71
	v_cndmask_b32_e64 v71, v71, 0, s[34:35]
	v_mul_f32_e32 v76, v77, v76
	v_sub_f32_e32 v77, v2, v142
	v_sub_f32_e32 v2, v2, v143
	v_mul_f32_e32 v77, 0x3fb8aa3b, v77
	v_mul_f32_e32 v2, 0x3fb8aa3b, v2
	v_exp_f32_e32 v77, v77
	v_exp_f32_e32 v2, v2
	v_mul_f32_e32 v76, v125, v76
	v_cndmask_b32_e64 v76, v76, 0, s[36:37]
	v_mul_f32_e32 v77, v78, v77
	v_mul_f32_e32 v2, v79, v2
	v_mul_f32_e32 v77, v126, v77
	v_mul_f32_e32 v2, v127, v2
	v_cndmask_b32_e64 v77, v77, 0, s[38:39]
	v_cndmask_b32_e64 v2, v2, 0, s[40:41]
	v_cvt_pk_bf16_f32 v70, v71, v76
	v_cvt_pk_bf16_f32 v71, v77, v2
	s_nop 0
	v_mfma_f32_16x16x32_bf16 v[92:95], v[68:71], v[120:123], v[84:87]
	v_mfma_f32_16x16x32_bf16 v[84:87], v[68:71], v[64:67], v[116:119]
	ds_read_b32 v2, v229 offset:64
	ds_read_b128 v[68:71], v232 offset:4352
	ds_read_b128 v[76:79], v232 offset:4368
	s_waitcnt lgkmcnt(2)
	v_sub_f32_e32 v3, v2, v148
	v_mul_f32_e32 v3, 0x3fb8aa3b, v3
	v_exp_f32_e32 v3, v3
	s_waitcnt lgkmcnt(1)
	v_mul_f32_e32 v3, v68, v3
	v_sub_f32_e32 v68, v2, v149
	v_mul_f32_e32 v68, 0x3fb8aa3b, v68
	v_exp_f32_e32 v68, v68
	v_mul_f32_e32 v3, v144, v3
	v_cndmask_b32_e64 v3, v3, 0, s[42:43]
	v_mul_f32_e32 v68, v69, v68
	v_sub_f32_e32 v69, v2, v150
	v_mul_f32_e32 v69, 0x3fb8aa3b, v69
	v_exp_f32_e32 v69, v69
	v_mul_f32_e32 v68, v145, v68
	v_cndmask_b32_e64 v68, 0, v68, s[44:45]
	v_cvt_pk_bf16_f32 v68, v3, v68
	v_mul_f32_e32 v69, v70, v69
	v_sub_f32_e32 v70, v2, v151
	v_mul_f32_e32 v70, 0x3fb8aa3b, v70
	v_exp_f32_e32 v70, v70
	v_mul_f32_e32 v69, v146, v69
	v_cndmask_b32_e64 v69, v69, 0, s[46:47]
	v_mul_f32_e32 v70, v71, v70
	v_sub_f32_e32 v71, v2, v140
	v_mul_f32_e32 v71, 0x3fb8aa3b, v71
	v_exp_f32_e32 v71, v71
	v_mul_f32_e32 v70, v147, v70
	v_cndmask_b32_e64 v70, v70, 0, s[48:49]
	v_cvt_pk_bf16_f32 v69, v69, v70
	s_waitcnt lgkmcnt(0)
	v_mul_f32_e32 v71, v76, v71
	v_sub_f32_e32 v76, v2, v141
	v_mul_f32_e32 v76, 0x3fb8aa3b, v76
	v_exp_f32_e32 v76, v76
	v_mul_f32_e32 v71, v124, v71
	v_cndmask_b32_e64 v71, v71, 0, s[50:51]
	v_mul_f32_e32 v76, v77, v76
	v_sub_f32_e32 v77, v2, v142
	v_sub_f32_e32 v2, v2, v143
	v_mul_f32_e32 v77, 0x3fb8aa3b, v77
	v_mul_f32_e32 v2, 0x3fb8aa3b, v2
	v_exp_f32_e32 v77, v77
	v_exp_f32_e32 v2, v2
	v_mul_f32_e32 v76, v125, v76
	v_cndmask_b32_e64 v76, v76, 0, s[52:53]
	v_mul_f32_e32 v77, v78, v77
	v_mul_f32_e32 v2, v79, v2
	v_mul_f32_e32 v77, v126, v77
	v_mul_f32_e32 v2, v127, v2
	v_cndmask_b32_e64 v77, v77, 0, s[54:55]
	v_cndmask_b32_e64 v2, v2, 0, s[56:57]
	v_cvt_pk_bf16_f32 v70, v71, v76
	v_cvt_pk_bf16_f32 v71, v77, v2
	s_nop 0
	v_mfma_f32_16x16x32_bf16 v[76:79], v[68:71], v[120:123], v[108:111]
	ds_read_b32 v2, v229 offset:128
	ds_read_b128 v[80:83], v232 offset:8704
	s_nop 0
	ds_read_b128 v[108:111], v232 offset:8720
	s_waitcnt lgkmcnt(2)
	v_sub_f32_e32 v3, v2, v148
	v_mul_f32_e32 v3, 0x3fb8aa3b, v3
	v_exp_f32_e32 v3, v3
	v_mfma_f32_16x16x32_bf16 v[68:71], v[68:71], v[64:67], v[112:115]
	s_waitcnt lgkmcnt(1)
	v_mul_f32_e32 v3, v80, v3
	v_sub_f32_e32 v80, v2, v149
	v_mul_f32_e32 v80, 0x3fb8aa3b, v80
	v_exp_f32_e32 v80, v80
	v_mul_f32_e32 v3, v144, v3
	v_mul_f32_e32 v80, v81, v80
	v_sub_f32_e32 v81, v2, v150
	v_mul_f32_e32 v81, 0x3fb8aa3b, v81
	v_exp_f32_e32 v81, v81
	v_mul_f32_e32 v80, v145, v80
	v_cvt_pk_bf16_f32 v80, v3, v80
	v_mul_f32_e32 v81, v82, v81
	v_sub_f32_e32 v82, v2, v151
	v_mul_f32_e32 v82, 0x3fb8aa3b, v82
	v_exp_f32_e32 v82, v82
	v_mul_f32_e32 v81, v146, v81
	v_mul_f32_e32 v82, v83, v82
	v_sub_f32_e32 v83, v2, v140
	v_mul_f32_e32 v83, 0x3fb8aa3b, v83
	v_exp_f32_e32 v83, v83
	v_mul_f32_e32 v82, v147, v82
	v_cvt_pk_bf16_f32 v81, v81, v82
	s_waitcnt lgkmcnt(0)
	v_mul_f32_e32 v83, v108, v83
	v_sub_f32_e32 v108, v2, v141
	v_mul_f32_e32 v108, 0x3fb8aa3b, v108
	v_exp_f32_e32 v108, v108
	v_mul_f32_e32 v83, v124, v83
	v_mul_f32_e32 v108, v109, v108
	v_sub_f32_e32 v109, v2, v142
	v_sub_f32_e32 v2, v2, v143
	v_mul_f32_e32 v109, 0x3fb8aa3b, v109
	v_mul_f32_e32 v2, 0x3fb8aa3b, v2
	v_exp_f32_e32 v109, v109
	v_exp_f32_e32 v2, v2
	v_mul_f32_e32 v108, v125, v108
	v_cvt_pk_bf16_f32 v82, v83, v108
	v_mul_f32_e32 v109, v110, v109
	v_mul_f32_e32 v2, v111, v2
	v_mul_f32_e32 v109, v126, v109
	v_mul_f32_e32 v2, v127, v2
	v_cvt_pk_bf16_f32 v83, v109, v2
	s_nop 0
	v_mfma_f32_16x16x32_bf16 v[132:135], v[80:83], v[120:123], v[100:103]
	v_mfma_f32_16x16x32_bf16 v[136:139], v[80:83], v[64:67], v[104:107]
	ds_read_b32 v2, v229 offset:192
	ds_read_b128 v[80:83], v232 offset:13056
	ds_read_b128 v[100:103], v232 offset:13072
	s_waitcnt lgkmcnt(2)
	v_sub_f32_e32 v3, v2, v148
	v_mul_f32_e32 v3, 0x3fb8aa3b, v3
	v_exp_f32_e32 v3, v3
	s_waitcnt lgkmcnt(1)
	v_mul_f32_e32 v3, v80, v3
	v_sub_f32_e32 v80, v2, v149
	v_mul_f32_e32 v80, 0x3fb8aa3b, v80
	v_exp_f32_e32 v80, v80
	v_mul_f32_e32 v3, v144, v3
	v_mul_f32_e32 v80, v81, v80
	v_sub_f32_e32 v81, v2, v150
	v_mul_f32_e32 v81, 0x3fb8aa3b, v81
	v_exp_f32_e32 v81, v81
	v_mul_f32_e32 v80, v145, v80
	v_mul_f32_e32 v81, v82, v81
	v_sub_f32_e32 v82, v2, v151
	v_mul_f32_e32 v82, 0x3fb8aa3b, v82
	v_exp_f32_e32 v82, v82
	v_mul_f32_e32 v81, v146, v81
	v_mul_f32_e32 v82, v83, v82
	v_sub_f32_e32 v83, v2, v140
	v_mul_f32_e32 v83, 0x3fb8aa3b, v83
	v_exp_f32_e32 v83, v83
	v_mul_f32_e32 v82, v147, v82
	s_waitcnt lgkmcnt(0)
	v_mul_f32_e32 v83, v100, v83
	v_sub_f32_e32 v100, v2, v141
	v_mul_f32_e32 v100, 0x3fb8aa3b, v100
	v_exp_f32_e32 v100, v100
	v_mul_f32_e32 v83, v124, v83
	v_mul_f32_e32 v100, v101, v100
	v_mul_f32_e32 v104, v125, v100
	v_sub_f32_e32 v100, v2, v142
	v_sub_f32_e32 v2, v2, v143
	v_mul_f32_e32 v100, 0x3fb8aa3b, v100
	v_mul_f32_e32 v2, 0x3fb8aa3b, v2
	v_exp_f32_e32 v100, v100
	v_exp_f32_e32 v2, v2
	v_mul_f32_e32 v100, v102, v100
	v_mul_f32_e32 v2, v103, v2
	v_mul_f32_e32 v105, v126, v100
	v_mul_f32_e32 v2, v127, v2
	v_cvt_pk_bf16_f32 v100, v3, v80
	v_cvt_pk_bf16_f32 v101, v81, v82
	v_cvt_pk_bf16_f32 v102, v83, v104
	v_cvt_pk_bf16_f32 v103, v105, v2
	v_sub_f32_e32 v2, v253, v148
	v_mfma_f32_16x16x32_bf16 v[80:83], v[100:103], v[120:123], v[88:91]
	v_sub_f32_e32 v3, v253, v149
	v_mul_f32_e32 v2, 0x3fb8aa3b, v2
	v_mul_f32_e32 v3, 0x3fb8aa3b, v3
	v_sub_f32_e32 v88, v253, v150
	v_mul_f32_e32 v88, 0x3fb8aa3b, v88
	v_exp_f32_e32 v88, v88
	v_mfma_f32_16x16x32_bf16 v[128:131], v[100:103], v[64:67], v[96:99]
	v_exp_f32_e32 v2, v2
	v_exp_f32_e32 v3, v3
	v_and_b32_e32 v89, 0xffff0000, v120
	v_mul_f32_e32 v96, v146, v88
	v_sub_f32_e32 v88, v253, v151
	v_mul_f32_e32 v88, 0x3fb8aa3b, v88
	v_exp_f32_e32 v88, v88
	v_mul_f32_e32 v2, v144, v2
	v_mul_f32_e32 v3, v145, v3
	v_lshlrev_b32_e32 v90, 16, v121
	v_mul_f32_e32 v97, v147, v88
	v_sub_f32_e32 v88, v253, v140
	v_mul_f32_e32 v88, 0x3fb8aa3b, v88
	v_exp_f32_e32 v88, v88
	v_lshlrev_b32_e32 v102, 16, v122
	v_mul_f32_e32 v89, v3, v89
	v_mul_f32_e32 v90, v96, v90
	v_mul_f32_e32 v98, v124, v88
	v_sub_f32_e32 v88, v253, v141
	v_mul_f32_e32 v88, 0x3fb8aa3b, v88
	v_exp_f32_e32 v88, v88
	v_and_b32_e32 v91, 0xffff0000, v121
	v_mul_f32_e32 v102, v98, v102
	v_and_b32_e32 v103, 0xffff0000, v122
	v_mul_f32_e32 v99, v125, v88
	v_sub_f32_e32 v88, v253, v142
	v_mul_f32_e32 v88, 0x3fb8aa3b, v88
	v_exp_f32_e32 v88, v88
	v_mul_f32_e32 v91, v97, v91
	v_mul_f32_e32 v103, v99, v103
	v_lshlrev_b32_e32 v104, 16, v123
	v_mul_f32_e32 v100, v126, v88
	v_sub_f32_e32 v88, v253, v143
	v_mul_f32_e32 v88, 0x3fb8aa3b, v88
	v_exp_f32_e32 v88, v88
	v_and_b32_e32 v105, 0xffff0000, v123
	v_mul_f32_e32 v104, v100, v104
	v_mul_f32_e32 v101, v127, v88
	v_lshlrev_b32_e32 v88, 16, v120
	v_mul_f32_e32 v88, v2, v88
	v_cvt_pk_bf16_f32 v88, v88, v89
	v_cvt_pk_bf16_f32 v89, v90, v91
	v_cvt_pk_bf16_f32 v90, v102, v103
	v_lshlrev_b32_e32 v102, 16, v64
	v_and_b32_e32 v64, 0xffff0000, v64
	v_mul_f32_e32 v3, v3, v64
	v_lshlrev_b32_e32 v64, 16, v65
	v_mul_f32_e32 v64, v96, v64
	v_lshlrev_b32_e32 v96, 16, v66
	v_and_b32_e32 v65, 0xffff0000, v65
	v_mul_f32_e32 v98, v98, v96
	v_and_b32_e32 v66, 0xffff0000, v66
	v_lshlrev_b32_e32 v96, 16, v67
	v_and_b32_e32 v67, 0xffff0000, v67
	v_mul_f32_e32 v65, v97, v65
	v_mul_f32_e32 v66, v99, v66
	v_mul_f32_e32 v99, v100, v96
	v_mul_f32_e32 v67, v101, v67
	v_mul_f32_e32 v105, v101, v105
	v_cvt_pk_bf16_f32 v91, v104, v105
	v_mul_f32_e32 v2, v2, v102
	v_cvt_pk_bf16_f32 v96, v2, v3
	v_cvt_pk_bf16_f32 v97, v64, v65
	v_cvt_pk_bf16_f32 v98, v98, v66
	v_cvt_pk_bf16_f32 v99, v99, v67
	ds_read_b128 v[64:67], v233 offset:34816
	s_waitcnt lgkmcnt(0)
	v_mfma_f32_16x16x32_bf16 v[2:5], v[64:67], v[88:91], v[4:7]
	v_mfma_f32_16x16x32_bf16 v[140:143], v[64:67], v[96:99], v[72:75]
	ds_read_b128 v[64:67], v233 offset:37120
	s_waitcnt lgkmcnt(0)
	v_mfma_f32_16x16x32_bf16 v[120:123], v[64:67], v[88:91], v[8:11]
	s_nop 2
	ds_read_b128 v[6:9], v233 offset:39424
	s_waitcnt lgkmcnt(0)
	v_mfma_f32_16x16x32_bf16 v[124:127], v[6:9], v[88:91], v[12:15]
	v_mfma_f32_16x16x32_bf16 v[24:27], v[6:9], v[96:99], v[24:27]
	ds_read_b128 v[6:9], v233 offset:41728
	s_waitcnt lgkmcnt(0)
	v_mfma_f32_16x16x32_bf16 v[116:119], v[6:9], v[88:91], v[20:23]
	v_mfma_f32_16x16x32_bf16 v[32:35], v[6:9], v[96:99], v[32:35]
	ds_read_b128 v[6:9], v233 offset:44032
	v_mfma_f32_16x16x32_bf16 v[16:19], v[64:67], v[96:99], v[16:19]
	s_waitcnt lgkmcnt(0)
	v_mfma_f32_16x16x32_bf16 v[64:67], v[6:9], v[88:91], v[28:31]
	v_mfma_f32_16x16x32_bf16 v[40:43], v[6:9], v[96:99], v[40:43]
	ds_read_b128 v[6:9], v233 offset:46336
	s_waitcnt lgkmcnt(0)
	v_mfma_f32_16x16x32_bf16 v[100:103], v[6:9], v[88:91], v[36:39]
	v_mfma_f32_16x16x32_bf16 v[48:51], v[6:9], v[96:99], v[48:51]
	ds_read_b128 v[6:9], v233 offset:48640
	s_waitcnt lgkmcnt(0)
	v_mfma_f32_16x16x32_bf16 v[104:107], v[6:9], v[88:91], v[44:47]
	v_mfma_f32_16x16x32_bf16 v[56:59], v[6:9], v[96:99], v[56:59]
	ds_read_b128 v[6:9], v233 offset:50944
	s_waitcnt lgkmcnt(0)
	v_mfma_f32_16x16x32_bf16 v[108:111], v[6:9], v[88:91], v[52:55]
	v_mfma_f32_16x16x32_bf16 v[112:115], v[6:9], v[96:99], v[60:63]
	ds_read_b128 v[44:47], v209 offset:128
	ds_read_b128 v[28:31], v209 offset:144
	ds_read_b128 v[36:39], v201 offset:128
	ds_read_b128 v[20:23], v201 offset:144
	ds_read_b128 v[10:13], v192 offset:53312
	ds_read_b128 v[6:9], v192 offset:55616
	ds_read_b32 v14, v229 offset:128
	ds_read_b128 v[52:55], v232 offset:8832
	ds_read_b128 v[60:63], v232 offset:8848
	s_waitcnt lgkmcnt(2)
	v_sub_f32_e32 v15, v14, v44
	v_mul_f32_e32 v15, 0x3fb8aa3b, v15
	v_exp_f32_e32 v15, v15
	s_waitcnt lgkmcnt(1)
	v_mul_f32_e32 v15, v52, v15
	v_sub_f32_e32 v52, v14, v45
	v_mul_f32_e32 v52, 0x3fb8aa3b, v52
	v_exp_f32_e32 v52, v52
	v_mul_f32_e32 v15, v36, v15
	v_cndmask_b32_e64 v15, v15, 0, s[24:25]
	v_mul_f32_e32 v52, v53, v52
	v_sub_f32_e32 v53, v14, v46
	v_mul_f32_e32 v53, 0x3fb8aa3b, v53
	v_exp_f32_e32 v53, v53
	v_mul_f32_e32 v52, v37, v52
	v_cndmask_b32_e64 v52, v52, 0, s[58:59]
	v_cvt_pk_bf16_f32 v52, v15, v52
	v_mul_f32_e32 v53, v54, v53
	v_sub_f32_e32 v54, v14, v47
	v_mul_f32_e32 v54, 0x3fb8aa3b, v54
	v_exp_f32_e32 v54, v54
	v_mul_f32_e32 v53, v38, v53
	v_cndmask_b32_e64 v53, v53, 0, s[60:61]
	v_mul_f32_e32 v54, v55, v54
	v_sub_f32_e32 v55, v14, v28
	v_mul_f32_e32 v55, 0x3fb8aa3b, v55
	v_exp_f32_e32 v55, v55
	v_mul_f32_e32 v54, v39, v54
	v_cndmask_b32_e64 v54, v54, 0, s[62:63]
	v_cvt_pk_bf16_f32 v53, v53, v54
	s_waitcnt lgkmcnt(0)
	v_mul_f32_e32 v55, v60, v55
	v_sub_f32_e32 v60, v14, v29
	v_mul_f32_e32 v60, 0x3fb8aa3b, v60
	v_exp_f32_e32 v60, v60
	v_mul_f32_e32 v55, v20, v55
	v_cndmask_b32_e64 v55, v55, 0, s[64:65]
	v_mul_f32_e32 v60, v61, v60
	v_sub_f32_e32 v61, v14, v30
	v_sub_f32_e32 v14, v14, v31
	v_mul_f32_e32 v61, 0x3fb8aa3b, v61
	v_mul_f32_e32 v14, 0x3fb8aa3b, v14
	v_exp_f32_e32 v61, v61
	v_exp_f32_e32 v14, v14
	v_mul_f32_e32 v60, v21, v60
	v_cndmask_b32_e64 v60, v60, 0, s[66:67]
	v_mul_f32_e32 v61, v62, v61
	v_mul_f32_e32 v14, v63, v14
	v_mul_f32_e32 v61, v22, v61
	v_mul_f32_e32 v14, v23, v14
	v_cndmask_b32_e64 v61, v61, 0, s[68:69]
	v_cndmask_b32_e64 v14, v14, 0, s[70:71]
	v_cvt_pk_bf16_f32 v54, v55, v60
	v_cvt_pk_bf16_f32 v55, v61, v14
	s_nop 0
	v_mfma_f32_16x16x32_bf16 v[96:99], v[52:55], v[10:13], v[132:135]
	v_mfma_f32_16x16x32_bf16 v[88:91], v[52:55], v[6:9], v[136:139]
	ds_read_b32 v14, v229 offset:192
	ds_read_b128 v[52:55], v232 offset:13184
	ds_read_b128 v[60:63], v232 offset:13200
	s_waitcnt lgkmcnt(2)
	v_sub_f32_e32 v15, v14, v44
	v_mul_f32_e32 v15, 0x3fb8aa3b, v15
	v_exp_f32_e32 v15, v15
	s_waitcnt lgkmcnt(1)
	v_mul_f32_e32 v15, v52, v15
	v_sub_f32_e32 v52, v14, v45
	v_mul_f32_e32 v52, 0x3fb8aa3b, v52
	v_exp_f32_e32 v52, v52
	v_mul_f32_e32 v15, v36, v15
	v_cndmask_b32_e64 v15, v15, 0, s[72:73]
	v_mul_f32_e32 v52, v53, v52
	v_sub_f32_e32 v53, v14, v46
	v_mul_f32_e32 v53, 0x3fb8aa3b, v53
	v_exp_f32_e32 v53, v53
	v_mul_f32_e32 v52, v37, v52
	v_cndmask_b32_e64 v52, v52, 0, s[74:75]
	v_cvt_pk_bf16_f32 v52, v15, v52
	v_mul_f32_e32 v53, v54, v53
	v_sub_f32_e32 v54, v14, v47
	v_mul_f32_e32 v54, 0x3fb8aa3b, v54
	v_exp_f32_e32 v54, v54
	v_mul_f32_e32 v53, v38, v53
	v_cndmask_b32_e64 v53, v53, 0, s[76:77]
	v_sub_f32_e32 v15, v253, v45
	v_mul_f32_e32 v54, v55, v54
	v_sub_f32_e32 v55, v14, v28
	v_mul_f32_e32 v55, 0x3fb8aa3b, v55
	v_exp_f32_e32 v55, v55
	v_sub_f32_e32 v28, v253, v28
	v_mul_f32_e32 v28, 0x3fb8aa3b, v28
	v_exp_f32_e32 v28, v28
	s_waitcnt lgkmcnt(0)
	v_mul_f32_e32 v55, v60, v55
	v_sub_f32_e32 v60, v14, v29
	v_mul_f32_e32 v60, 0x3fb8aa3b, v60
	v_exp_f32_e32 v60, v60
	v_mul_f32_e32 v55, v20, v55
	v_mul_f32_e32 v20, v20, v28
	v_sub_f32_e32 v28, v253, v29
	v_mul_f32_e32 v60, v61, v60
	v_sub_f32_e32 v61, v14, v30
	v_sub_f32_e32 v14, v14, v31
	v_mul_f32_e32 v14, 0x3fb8aa3b, v14
	v_mul_f32_e32 v61, 0x3fb8aa3b, v61
	v_exp_f32_e32 v14, v14
	v_exp_f32_e32 v61, v61
	v_mul_f32_e32 v28, 0x3fb8aa3b, v28
	v_exp_f32_e32 v28, v28
	v_mul_f32_e32 v14, v63, v14
	v_mul_f32_e32 v54, v39, v54
	v_mul_f32_e32 v61, v62, v61
	v_mul_f32_e32 v14, v23, v14
	v_cndmask_b32_e64 v54, v54, 0, s[78:79]
	v_cndmask_b32_e64 v55, v55, 0, s[80:81]
	v_mul_f32_e32 v60, v21, v60
	v_mul_f32_e32 v61, v22, v61
	v_cndmask_b32_e64 v14, v14, 0, s[86:87]
	v_mul_f32_e32 v21, v21, v28
	v_sub_f32_e32 v28, v253, v30
	v_cndmask_b32_e64 v60, v60, 0, s[82:83]
	v_cndmask_b32_e64 v61, v61, 0, s[84:85]
	v_cvt_pk_bf16_f32 v53, v53, v54
	v_cvt_pk_bf16_f32 v54, v55, v60
	v_cvt_pk_bf16_f32 v55, v61, v14
	v_sub_f32_e32 v14, v253, v44
	v_mul_f32_e32 v15, 0x3fb8aa3b, v15
	v_mul_f32_e32 v28, 0x3fb8aa3b, v28
	v_mul_f32_e32 v14, 0x3fb8aa3b, v14
	v_exp_f32_e32 v15, v15
	v_exp_f32_e32 v28, v28
	v_exp_f32_e32 v14, v14
	v_mfma_f32_16x16x32_bf16 v[80:83], v[52:55], v[10:13], v[80:83]
	v_mul_f32_e32 v15, v37, v15
	v_sub_f32_e32 v37, v253, v47
	v_mul_f32_e32 v22, v22, v28
	v_sub_f32_e32 v28, v253, v31
	v_mul_f32_e32 v14, v36, v14
	v_sub_f32_e32 v36, v253, v46
	v_mul_f32_e32 v37, 0x3fb8aa3b, v37
	v_mul_f32_e32 v28, 0x3fb8aa3b, v28
	v_mul_f32_e32 v36, 0x3fb8aa3b, v36
	v_exp_f32_e32 v37, v37
	v_exp_f32_e32 v28, v28
	v_exp_f32_e32 v36, v36
	v_lshlrev_b32_e32 v29, 16, v11
	v_mul_f32_e32 v37, v39, v37
	v_mul_f32_e32 v23, v23, v28
	v_lshlrev_b32_e32 v28, 16, v10
	v_and_b32_e32 v10, 0xffff0000, v10
	v_and_b32_e32 v11, 0xffff0000, v11
	v_lshlrev_b32_e32 v30, 16, v12
	v_and_b32_e32 v12, 0xffff0000, v12
	v_lshlrev_b32_e32 v31, 16, v13
	v_and_b32_e32 v13, 0xffff0000, v13
	v_mul_f32_e32 v36, v38, v36
	v_mul_f32_e32 v10, v15, v10
	v_mul_f32_e32 v11, v37, v11
	v_mul_f32_e32 v12, v21, v12
	v_mul_f32_e32 v13, v23, v13
	v_mfma_f32_16x16x32_bf16 v[72:75], v[52:55], v[6:9], v[128:131]
	v_mul_f32_e32 v28, v14, v28
	v_mul_f32_e32 v29, v36, v29
	v_mul_f32_e32 v30, v20, v30
	v_mul_f32_e32 v31, v22, v31
	v_cvt_pk_bf16_f32 v60, v28, v10
	v_cvt_pk_bf16_f32 v61, v29, v11
	v_cvt_pk_bf16_f32 v62, v30, v12
	v_cvt_pk_bf16_f32 v63, v31, v13
	v_lshlrev_b32_e32 v10, 16, v6
	v_lshlrev_b32_e32 v11, 16, v7
	v_lshlrev_b32_e32 v12, 16, v8
	v_and_b32_e32 v8, 0xffff0000, v8
	v_lshlrev_b32_e32 v13, 16, v9
	v_and_b32_e32 v9, 0xffff0000, v9
	v_mul_f32_e32 v10, v14, v10
	v_and_b32_e32 v6, 0xffff0000, v6
	v_mul_f32_e32 v11, v36, v11
	v_and_b32_e32 v7, 0xffff0000, v7
	v_mul_f32_e32 v8, v21, v8
	v_mul_f32_e32 v9, v23, v9
	v_mul_f32_e32 v6, v15, v6
	v_mul_f32_e32 v7, v37, v7
	v_mul_f32_e32 v12, v20, v12
	v_mul_f32_e32 v13, v22, v13
	v_cvt_pk_bf16_f32 v128, v10, v6
	v_cvt_pk_bf16_f32 v129, v11, v7
	v_cvt_pk_bf16_f32 v130, v12, v8
	v_cvt_pk_bf16_f32 v131, v13, v9
	ds_read_b128 v[8:11], v233 offset:34880
	ds_read_b128 v[20:23], v233 offset:37184
	ds_read_b128 v[28:31], v233 offset:39488
	ds_read_b128 v[36:39], v233 offset:41792
	ds_read_b128 v[44:47], v233 offset:44096
	ds_read_b128 v[52:55], v233 offset:46400
	s_waitcnt lgkmcnt(4)
	v_mfma_f32_16x16x32_bf16 v[12:15], v[20:23], v[60:63], v[120:123]
	v_mfma_f32_16x16x32_bf16 v[16:19], v[20:23], v[128:131], v[16:19]
	s_waitcnt lgkmcnt(3)
	v_mfma_f32_16x16x32_bf16 v[20:23], v[28:31], v[60:63], v[124:127]
	v_mfma_f32_16x16x32_bf16 v[24:27], v[28:31], v[128:131], v[24:27]
	s_waitcnt lgkmcnt(2)
	v_mfma_f32_16x16x32_bf16 v[28:31], v[36:39], v[60:63], v[116:119]
	v_mfma_f32_16x16x32_bf16 v[32:35], v[36:39], v[128:131], v[32:35]
	s_waitcnt lgkmcnt(1)
	v_mfma_f32_16x16x32_bf16 v[36:39], v[44:47], v[60:63], v[64:67]
	s_nop 2
	ds_read_b128 v[64:67], v233 offset:48704
	v_mfma_f32_16x16x32_bf16 v[4:7], v[8:11], v[60:63], v[2:5]
	v_mfma_f32_16x16x32_bf16 v[40:43], v[44:47], v[128:131], v[40:43]
	s_nop 1
	ds_read_b64 v[2:3], v234 offset:53248
	s_waitcnt lgkmcnt(2)
	v_mfma_f32_16x16x32_bf16 v[44:47], v[52:55], v[60:63], v[100:103]
	v_mfma_f32_16x16x32_bf16 v[48:51], v[52:55], v[128:131], v[48:51]
	s_nop 1
	ds_read_u16 v102, v235
	ds_read_u16 v103, v235 offset:528
	s_waitcnt lgkmcnt(2)
	v_lshlrev_b32_e32 v100, 16, v2
	v_mfma_f32_16x16x32_bf16 v[52:55], v[64:67], v[60:63], v[104:107]
	v_and_b32_e32 v101, 0xffff0000, v2
	s_waitcnt lgkmcnt(1)
	v_lshlrev_b32_e32 v102, 16, v102
	s_waitcnt lgkmcnt(0)
	v_lshlrev_b32_e32 v103, 16, v103
	v_mfma_f32_16x16x32_bf16 v[56:59], v[64:67], v[128:131], v[56:59]
	ds_read_b128 v[64:67], v233 offset:51008
	v_pk_fma_f32 v[92:93], v[154:155], v[100:101], v[92:93]
	v_pk_mul_f32 v[100:101], v[102:103], s[96:97] op_sel_hi:[1,0]
	v_lshlrev_b32_e32 v2, 16, v3
	v_exp_f32_e32 v100, v100
	v_exp_f32_e32 v101, v101
	v_and_b32_e32 v3, 0xffff0000, v3
	v_pk_fma_f32 v[2:3], v[154:155], v[2:3], v[94:95]
	v_mfma_f32_16x16x32_bf16 v[8:11], v[8:11], v[128:131], v[140:143]
	v_add_f32_e64 v100, v100, 1.0
	v_add_f32_e64 v101, v101, 1.0
	v_rcp_f32_e32 v100, v100
	v_rcp_f32_e32 v101, v101
	s_waitcnt lgkmcnt(0)
	v_mfma_f32_16x16x32_bf16 v[60:63], v[64:67], v[60:63], v[108:111]
	v_mul_f32_e64 v100, v100, v102
	v_mul_f32_e64 v101, v101, v103
	v_pk_mul_f32 v[92:93], v[92:93], v[100:101]
	v_mfma_f32_16x16x32_bf16 v[64:67], v[64:67], v[128:131], v[112:115]
	v_cvt_pk_bf16_f32 v102, v92, v93
	ds_write_b16 v235, v102
	ds_write_b16_d16_hi v235, v102 offset:528
	ds_read_u16 v92, v235 offset:1056
	ds_read_u16 v93, v235 offset:1584
	s_waitcnt lgkmcnt(1)
	v_lshlrev_b32_e32 v92, 16, v92
	s_waitcnt lgkmcnt(0)
	v_lshlrev_b32_e32 v93, 16, v93
	v_pk_mul_f32 v[94:95], v[92:93], s[96:97] op_sel_hi:[1,0]
	s_nop 0
	v_exp_f32_e32 v94, v94
	v_exp_f32_e32 v95, v95
	s_nop 0
	v_pk_add_f32 v[94:95], v[94:95], 1.0 op_sel_hi:[1,0]
	s_nop 0
	v_rcp_f32_e32 v94, v94
	v_rcp_f32_e32 v95, v95
	s_nop 0
	v_pk_mul_f32 v[92:93], v[94:95], v[92:93]
	s_nop 0
	v_pk_mul_f32 v[2:3], v[2:3], v[92:93]
	s_nop 0
	v_cvt_pk_bf16_f32 v103, v2, v3
	ds_write_b16 v235, v103 offset:1056
	ds_write_b16_d16_hi v235, v103 offset:1584
	ds_read_b64 v[2:3], v234 offset:55552
	ds_read_u16 v94, v235 offset:32
	ds_read_u16 v95, v235 offset:560
	s_waitcnt lgkmcnt(2)
	v_lshlrev_b32_e32 v92, 16, v2
	v_and_b32_e32 v93, 0xffff0000, v2
	s_waitcnt lgkmcnt(1)
	v_lshlrev_b32_e32 v94, 16, v94
	s_waitcnt lgkmcnt(0)
	v_lshlrev_b32_e32 v95, 16, v95
	v_pk_fma_f32 v[84:85], v[154:155], v[92:93], v[84:85]
	v_pk_mul_f32 v[92:93], v[94:95], s[96:97] op_sel_hi:[1,0]
	v_lshlrev_b32_e32 v2, 16, v3
	v_exp_f32_e32 v92, v92
	v_exp_f32_e32 v93, v93
	v_and_b32_e32 v3, 0xffff0000, v3
	v_pk_fma_f32 v[2:3], v[154:155], v[2:3], v[86:87]
	v_pk_add_f32 v[92:93], v[92:93], 1.0 op_sel_hi:[1,0]
	s_nop 0
	v_rcp_f32_e32 v92, v92
	v_rcp_f32_e32 v93, v93
	s_nop 0
	v_pk_mul_f32 v[92:93], v[92:93], v[94:95]
	s_nop 0
	v_pk_mul_f32 v[84:85], v[84:85], v[92:93]
	s_nop 0
	v_cvt_pk_bf16_f32 v92, v84, v85
	ds_write_b16 v235, v92 offset:32
	ds_write_b16_d16_hi v235, v92 offset:560
	ds_read_u16 v84, v235 offset:1088
	ds_read_u16 v85, v235 offset:1616
	s_waitcnt lgkmcnt(1)
	v_lshlrev_b32_e32 v84, 16, v84
	s_waitcnt lgkmcnt(0)
	v_lshlrev_b32_e32 v85, 16, v85
	v_pk_mul_f32 v[86:87], v[84:85], s[96:97] op_sel_hi:[1,0]
	s_nop 0
	v_exp_f32_e32 v86, v86
	v_exp_f32_e32 v87, v87
	s_nop 0
	v_pk_add_f32 v[86:87], v[86:87], 1.0 op_sel_hi:[1,0]
	s_nop 0
	v_rcp_f32_e32 v86, v86
	v_rcp_f32_e32 v87, v87
	s_nop 0
	v_pk_mul_f32 v[84:85], v[86:87], v[84:85]
	s_nop 0
	v_pk_mul_f32 v[2:3], v[2:3], v[84:85]
	v_lshlrev_b32_e32 v84, 16, v92
	v_cvt_pk_bf16_f32 v93, v2, v3
	v_and_b32_e32 v3, 64, v199
	v_xor_b32_e32 v2, 1, v199
	v_add_u32_e32 v3, 64, v3
	v_cmp_lt_i32_e32 vcc, v2, v3
	ds_write_b16 v235, v93 offset:1088
	ds_write_b16_d16_hi v235, v93 offset:1616
	v_cndmask_b32_e32 v2, v199, v2, vcc
	v_lshlrev_b32_e32 v101, 2, v2
	v_xor_b32_e32 v2, 2, v199
	v_cmp_lt_i32_e32 vcc, v2, v3
	v_and_b32_e32 v85, 0xffff0000, v92
	v_lshlrev_b32_e32 v92, 16, v93
	v_cndmask_b32_e32 v2, v199, v2, vcc
	v_lshlrev_b32_e32 v100, 2, v2
	v_xor_b32_e32 v2, 4, v199
	v_cmp_lt_i32_e32 vcc, v2, v3
	v_and_b32_e32 v93, 0xffff0000, v93
	v_pk_mul_f32 v[84:85], v[84:85], v[84:85]
	v_cndmask_b32_e32 v2, v199, v2, vcc
	v_lshlrev_b32_e32 v95, 2, v2
	v_xor_b32_e32 v2, 8, v199
	v_cmp_lt_i32_e32 vcc, v2, v3
	v_and_b32_e32 v3, 0xffff0000, v102
	v_lshlrev_b32_e32 v86, 16, v103
	v_cndmask_b32_e32 v2, v199, v2, vcc
	v_lshlrev_b32_e32 v94, 2, v2
	v_lshlrev_b32_e32 v2, 16, v102
	v_and_b32_e32 v87, 0xffff0000, v103
	v_pk_mul_f32 v[92:93], v[92:93], v[92:93]
	v_pk_fma_f32 v[2:3], v[2:3], v[2:3], v[84:85]
	v_pk_fma_f32 v[86:87], v[86:87], v[86:87], v[92:93]
	s_nop 0
	v_add_u32_e32 v102, s12, v156
	v_add_f32_dpp v2, v2, v2 quad_perm:[1,0,3,2] row_mask:0xf bank_mask:0xf
	v_add_f32_dpp v3, v3, v3 quad_perm:[1,0,3,2] row_mask:0xf bank_mask:0xf
	v_add_f32_dpp v86, v86, v86 quad_perm:[1,0,3,2] row_mask:0xf bank_mask:0xf
	v_add_f32_dpp v87, v87, v87 quad_perm:[1,0,3,2] row_mask:0xf bank_mask:0xf
	v_add_f32_dpp v2, v2, v2 quad_perm:[2,3,0,1] row_mask:0xf bank_mask:0xf
	v_add_f32_dpp v3, v3, v3 quad_perm:[2,3,0,1] row_mask:0xf bank_mask:0xf
	v_add_f32_dpp v86, v86, v86 quad_perm:[2,3,0,1] row_mask:0xf bank_mask:0xf
	v_add_f32_dpp v87, v87, v87 quad_perm:[2,3,0,1] row_mask:0xf bank_mask:0xf
	v_add_f32_dpp v2, v2, v2 row_half_mirror row_mask:0xf bank_mask:0xf
	v_add_f32_dpp v3, v3, v3 row_half_mirror row_mask:0xf bank_mask:0xf
	v_add_f32_dpp v86, v86, v86 row_half_mirror row_mask:0xf bank_mask:0xf
	v_add_f32_dpp v87, v87, v87 row_half_mirror row_mask:0xf bank_mask:0xf
	v_add_f32_dpp v84, v2, v2 row_mirror row_mask:0xf bank_mask:0xf
	v_add_f32_dpp v85, v3, v3 row_mirror row_mask:0xf bank_mask:0xf
	v_add_f32_dpp v86, v86, v86 row_mirror row_mask:0xf bank_mask:0xf
	v_add_f32_dpp v87, v87, v87 row_mirror row_mask:0xf bank_mask:0xf
	s_and_saveexec_b64 s[94:95], s[10:11]
	s_cbranch_execz .LBB0_382
	ds_write_b128 v102, v[84:87]
.LBB0_382:
	s_or_b64 exec, exec, s[94:95]
	ds_read_b64 v[2:3], v234 offset:53280
	ds_read_u16 v86, v235 offset:8448
	ds_read_u16 v87, v235 offset:8976
	s_waitcnt lgkmcnt(2)
	v_lshlrev_b32_e32 v84, 16, v2
	v_and_b32_e32 v85, 0xffff0000, v2
	s_waitcnt lgkmcnt(1)
	v_lshlrev_b32_e32 v86, 16, v86
	s_waitcnt lgkmcnt(0)
	v_lshlrev_b32_e32 v87, 16, v87
	v_pk_fma_f32 v[76:77], v[154:155], v[84:85], v[76:77]
	v_pk_mul_f32 v[84:85], v[86:87], s[96:97] op_sel_hi:[1,0]
	v_lshlrev_b32_e32 v2, 16, v3
	v_exp_f32_e32 v84, v84
	v_exp_f32_e32 v85, v85
	v_and_b32_e32 v3, 0xffff0000, v3
	v_pk_fma_f32 v[2:3], v[154:155], v[2:3], v[78:79]
	v_pk_add_f32 v[84:85], v[84:85], 1.0 op_sel_hi:[1,0]
	s_nop 0
	v_rcp_f32_e32 v84, v84
	v_rcp_f32_e32 v85, v85
	s_nop 0
	v_pk_mul_f32 v[84:85], v[84:85], v[86:87]
	s_nop 0
	v_pk_mul_f32 v[76:77], v[76:77], v[84:85]
	s_nop 0
	v_cvt_pk_bf16_f32 v84, v76, v77
	ds_write_b16 v235, v84 offset:8448
	ds_write_b16_d16_hi v235, v84 offset:8976
	ds_read_u16 v76, v235 offset:9504
	ds_read_u16 v77, v235 offset:10032
	s_waitcnt lgkmcnt(1)
	v_lshlrev_b32_e32 v76, 16, v76
	s_waitcnt lgkmcnt(0)
	v_lshlrev_b32_e32 v77, 16, v77
	v_pk_mul_f32 v[78:79], v[76:77], s[96:97] op_sel_hi:[1,0]
	s_nop 0
	v_exp_f32_e32 v78, v78
	v_exp_f32_e32 v79, v79
	s_nop 0
	v_pk_add_f32 v[78:79], v[78:79], 1.0 op_sel_hi:[1,0]
	s_nop 0
	v_rcp_f32_e32 v78, v78
	v_rcp_f32_e32 v79, v79
	s_nop 0
	v_pk_mul_f32 v[76:77], v[78:79], v[76:77]
	s_nop 0
	v_pk_mul_f32 v[2:3], v[2:3], v[76:77]
	s_nop 0
	v_cvt_pk_bf16_f32 v85, v2, v3
	ds_write_b16 v235, v85 offset:9504
	ds_write_b16_d16_hi v235, v85 offset:10032
	ds_read_b64 v[2:3], v234 offset:55584
	ds_read_u16 v78, v235 offset:8480
	ds_read_u16 v79, v235 offset:9008
	s_waitcnt lgkmcnt(2)
	v_lshlrev_b32_e32 v76, 16, v2
	v_and_b32_e32 v77, 0xffff0000, v2
	s_waitcnt lgkmcnt(1)
	v_lshlrev_b32_e32 v78, 16, v78
	s_waitcnt lgkmcnt(0)
	v_lshlrev_b32_e32 v79, 16, v79
	v_pk_fma_f32 v[68:69], v[154:155], v[76:77], v[68:69]
	v_pk_mul_f32 v[76:77], v[78:79], s[96:97] op_sel_hi:[1,0]
	v_lshlrev_b32_e32 v2, 16, v3
	v_exp_f32_e32 v76, v76
	v_exp_f32_e32 v77, v77
	v_and_b32_e32 v3, 0xffff0000, v3
	v_pk_fma_f32 v[2:3], v[154:155], v[2:3], v[70:71]
	v_pk_add_f32 v[76:77], v[76:77], 1.0 op_sel_hi:[1,0]
	s_nop 0
	v_rcp_f32_e32 v76, v76
	v_rcp_f32_e32 v77, v77
	s_nop 0
	v_pk_mul_f32 v[76:77], v[76:77], v[78:79]
	s_nop 0
	v_pk_mul_f32 v[68:69], v[68:69], v[76:77]
	s_nop 0
	v_cvt_pk_bf16_f32 v76, v68, v69
	ds_write_b16 v235, v76 offset:8480
	ds_write_b16_d16_hi v235, v76 offset:9008
	ds_read_u16 v68, v235 offset:9536
	ds_read_u16 v69, v235 offset:10064
	s_waitcnt lgkmcnt(1)
	v_lshlrev_b32_e32 v68, 16, v68
	s_waitcnt lgkmcnt(0)
	v_lshlrev_b32_e32 v69, 16, v69
	v_pk_mul_f32 v[70:71], v[68:69], s[96:97] op_sel_hi:[1,0]
	s_nop 0
	v_exp_f32_e32 v70, v70
	v_exp_f32_e32 v71, v71
	s_nop 0
	v_pk_add_f32 v[70:71], v[70:71], 1.0 op_sel_hi:[1,0]
	s_nop 0
	v_rcp_f32_e32 v70, v70
	v_rcp_f32_e32 v71, v71
	s_nop 0
	v_pk_mul_f32 v[68:69], v[70:71], v[68:69]
	s_nop 0
	v_pk_mul_f32 v[2:3], v[2:3], v[68:69]
	v_lshlrev_b32_e32 v68, 16, v76
	v_cvt_pk_bf16_f32 v77, v2, v3
	ds_write_b16 v235, v77 offset:9536
	ds_write_b16_d16_hi v235, v77 offset:10064
	v_and_b32_e32 v69, 0xffff0000, v76
	v_lshlrev_b32_e32 v76, 16, v77
	v_and_b32_e32 v77, 0xffff0000, v77
	v_lshlrev_b32_e32 v2, 16, v84
	v_and_b32_e32 v3, 0xffff0000, v84
	v_pk_mul_f32 v[68:69], v[68:69], v[68:69]
	v_lshlrev_b32_e32 v70, 16, v85
	v_and_b32_e32 v71, 0xffff0000, v85
	v_pk_mul_f32 v[76:77], v[76:77], v[76:77]
	v_pk_fma_f32 v[2:3], v[2:3], v[2:3], v[68:69]
	v_pk_fma_f32 v[70:71], v[70:71], v[70:71], v[76:77]
	s_nop 0
	v_add_f32_dpp v2, v2, v2 quad_perm:[1,0,3,2] row_mask:0xf bank_mask:0xf
	v_add_f32_dpp v3, v3, v3 quad_perm:[1,0,3,2] row_mask:0xf bank_mask:0xf
	v_add_f32_dpp v70, v70, v70 quad_perm:[1,0,3,2] row_mask:0xf bank_mask:0xf
	v_add_f32_dpp v71, v71, v71 quad_perm:[1,0,3,2] row_mask:0xf bank_mask:0xf
	v_add_f32_dpp v2, v2, v2 quad_perm:[2,3,0,1] row_mask:0xf bank_mask:0xf
	v_add_f32_dpp v3, v3, v3 quad_perm:[2,3,0,1] row_mask:0xf bank_mask:0xf
	v_add_f32_dpp v70, v70, v70 quad_perm:[2,3,0,1] row_mask:0xf bank_mask:0xf
	v_add_f32_dpp v71, v71, v71 quad_perm:[2,3,0,1] row_mask:0xf bank_mask:0xf
	v_add_f32_dpp v2, v2, v2 row_half_mirror row_mask:0xf bank_mask:0xf
	v_add_f32_dpp v3, v3, v3 row_half_mirror row_mask:0xf bank_mask:0xf
	v_add_f32_dpp v70, v70, v70 row_half_mirror row_mask:0xf bank_mask:0xf
	v_add_f32_dpp v71, v71, v71 row_half_mirror row_mask:0xf bank_mask:0xf
	v_add_f32_dpp v68, v2, v2 row_mirror row_mask:0xf bank_mask:0xf
	v_add_f32_dpp v69, v3, v3 row_mirror row_mask:0xf bank_mask:0xf
	v_add_f32_dpp v70, v70, v70 row_mirror row_mask:0xf bank_mask:0xf
	v_add_f32_dpp v71, v71, v71 row_mirror row_mask:0xf bank_mask:0xf
	s_and_saveexec_b64 s[94:95], s[10:11]
	s_cbranch_execz .LBB0_384
	ds_write_b128 v102, v[68:71] offset:64
.LBB0_384:
	s_or_b64 exec, exec, s[94:95]
	ds_read_b64 v[2:3], v234 offset:53312
	ds_read_u16 v70, v235 offset:16896
	ds_read_u16 v71, v235 offset:17424
	s_waitcnt lgkmcnt(2)
	v_lshlrev_b32_e32 v68, 16, v2
	s_waitcnt lgkmcnt(1)
	v_lshlrev_b32_e32 v70, 16, v70
	s_waitcnt lgkmcnt(0)
	v_lshlrev_b32_e32 v71, 16, v71
	v_pk_mul_f32 v[76:77], v[70:71], s[96:97] op_sel_hi:[1,0]
	v_and_b32_e32 v69, 0xffff0000, v2
	v_exp_f32_e32 v76, v76
	v_exp_f32_e32 v77, v77
	v_pk_fma_f32 v[68:69], v[154:155], v[68:69], v[96:97]
	v_lshlrev_b32_e32 v2, 16, v3
	v_and_b32_e32 v3, 0xffff0000, v3
	v_pk_add_f32 v[76:77], v[76:77], 1.0 op_sel_hi:[1,0]
	v_pk_fma_f32 v[2:3], v[154:155], v[2:3], v[98:99]
	v_rcp_f32_e32 v76, v76
	v_rcp_f32_e32 v77, v77
	s_nop 0
	v_pk_mul_f32 v[70:71], v[76:77], v[70:71]
	s_nop 0
	v_pk_mul_f32 v[68:69], v[68:69], v[70:71]
	s_nop 0
	v_cvt_pk_bf16_f32 v78, v68, v69
	ds_write_b16 v235, v78 offset:16896
	ds_write_b16_d16_hi v235, v78 offset:17424
	ds_read_u16 v68, v235 offset:17952
	ds_read_u16 v69, v235 offset:18480
	s_waitcnt lgkmcnt(1)
	v_lshlrev_b32_e32 v68, 16, v68
	s_waitcnt lgkmcnt(0)
	v_lshlrev_b32_e32 v69, 16, v69
	v_pk_mul_f32 v[70:71], v[68:69], s[96:97] op_sel_hi:[1,0]
	s_nop 0
	v_exp_f32_e32 v70, v70
	v_exp_f32_e32 v71, v71
	s_nop 0
	v_pk_add_f32 v[70:71], v[70:71], 1.0 op_sel_hi:[1,0]
	s_nop 0
	v_rcp_f32_e32 v70, v70
	v_rcp_f32_e32 v71, v71
	s_nop 0
	v_pk_mul_f32 v[68:69], v[70:71], v[68:69]
	s_nop 0
	v_pk_mul_f32 v[2:3], v[2:3], v[68:69]
	s_nop 0
	v_cvt_pk_bf16_f32 v79, v2, v3
	ds_write_b16 v235, v79 offset:17952
	ds_write_b16_d16_hi v235, v79 offset:18480
	ds_read_b64 v[2:3], v234 offset:55616
	ds_read_u16 v70, v235 offset:16928
	ds_read_u16 v71, v235 offset:17456
	s_waitcnt lgkmcnt(2)
	v_lshlrev_b32_e32 v68, 16, v2
	s_waitcnt lgkmcnt(1)
	v_lshlrev_b32_e32 v70, 16, v70
	s_waitcnt lgkmcnt(0)
	v_lshlrev_b32_e32 v71, 16, v71
	v_pk_mul_f32 v[76:77], v[70:71], s[96:97] op_sel_hi:[1,0]
	v_and_b32_e32 v69, 0xffff0000, v2
	v_exp_f32_e32 v76, v76
	v_exp_f32_e32 v77, v77
	v_pk_fma_f32 v[68:69], v[154:155], v[68:69], v[88:89]
	v_lshlrev_b32_e32 v2, 16, v3
	v_and_b32_e32 v3, 0xffff0000, v3
	v_pk_add_f32 v[76:77], v[76:77], 1.0 op_sel_hi:[1,0]
	v_pk_fma_f32 v[2:3], v[154:155], v[2:3], v[90:91]
	v_rcp_f32_e32 v76, v76
	v_rcp_f32_e32 v77, v77
	s_nop 0
	v_pk_mul_f32 v[70:71], v[76:77], v[70:71]
	s_nop 0
	v_pk_mul_f32 v[68:69], v[68:69], v[70:71]
	s_nop 0
	v_cvt_pk_bf16_f32 v76, v68, v69
	ds_write_b16 v235, v76 offset:16928
	ds_write_b16_d16_hi v235, v76 offset:17456
	ds_read_u16 v68, v235 offset:17984
	ds_read_u16 v69, v235 offset:18512
	s_waitcnt lgkmcnt(1)
	v_lshlrev_b32_e32 v68, 16, v68
	s_waitcnt lgkmcnt(0)
	v_lshlrev_b32_e32 v69, 16, v69
	v_pk_mul_f32 v[70:71], v[68:69], s[96:97] op_sel_hi:[1,0]
	s_nop 0
	v_exp_f32_e32 v70, v70
	v_exp_f32_e32 v71, v71
	s_nop 0
	v_pk_add_f32 v[70:71], v[70:71], 1.0 op_sel_hi:[1,0]
	s_nop 0
	v_rcp_f32_e32 v70, v70
	v_rcp_f32_e32 v71, v71
	s_nop 0
	v_pk_mul_f32 v[68:69], v[70:71], v[68:69]
	s_nop 0
	v_pk_mul_f32 v[2:3], v[2:3], v[68:69]
	v_lshlrev_b32_e32 v68, 16, v76
	v_cvt_pk_bf16_f32 v77, v2, v3
	ds_write_b16 v235, v77 offset:17984
	ds_write_b16_d16_hi v235, v77 offset:18512
	v_and_b32_e32 v69, 0xffff0000, v76
	v_lshlrev_b32_e32 v76, 16, v77
	v_and_b32_e32 v77, 0xffff0000, v77
	v_lshlrev_b32_e32 v2, 16, v78
	v_and_b32_e32 v3, 0xffff0000, v78
	v_pk_mul_f32 v[68:69], v[68:69], v[68:69]
	v_lshlrev_b32_e32 v70, 16, v79
	v_and_b32_e32 v71, 0xffff0000, v79
	v_pk_mul_f32 v[76:77], v[76:77], v[76:77]
	v_pk_fma_f32 v[2:3], v[2:3], v[2:3], v[68:69]
	v_pk_fma_f32 v[70:71], v[70:71], v[70:71], v[76:77]
	s_nop 0
	v_add_f32_dpp v2, v2, v2 quad_perm:[1,0,3,2] row_mask:0xf bank_mask:0xf
	v_add_f32_dpp v3, v3, v3 quad_perm:[1,0,3,2] row_mask:0xf bank_mask:0xf
	v_add_f32_dpp v70, v70, v70 quad_perm:[1,0,3,2] row_mask:0xf bank_mask:0xf
	v_add_f32_dpp v71, v71, v71 quad_perm:[1,0,3,2] row_mask:0xf bank_mask:0xf
	v_add_f32_dpp v2, v2, v2 quad_perm:[2,3,0,1] row_mask:0xf bank_mask:0xf
	v_add_f32_dpp v3, v3, v3 quad_perm:[2,3,0,1] row_mask:0xf bank_mask:0xf
	v_add_f32_dpp v70, v70, v70 quad_perm:[2,3,0,1] row_mask:0xf bank_mask:0xf
	v_add_f32_dpp v71, v71, v71 quad_perm:[2,3,0,1] row_mask:0xf bank_mask:0xf
	v_add_f32_dpp v2, v2, v2 row_half_mirror row_mask:0xf bank_mask:0xf
	v_add_f32_dpp v3, v3, v3 row_half_mirror row_mask:0xf bank_mask:0xf
	v_add_f32_dpp v70, v70, v70 row_half_mirror row_mask:0xf bank_mask:0xf
	v_add_f32_dpp v71, v71, v71 row_half_mirror row_mask:0xf bank_mask:0xf
	v_add_f32_dpp v68, v2, v2 row_mirror row_mask:0xf bank_mask:0xf
	v_add_f32_dpp v69, v3, v3 row_mirror row_mask:0xf bank_mask:0xf
	v_add_f32_dpp v70, v70, v70 row_mirror row_mask:0xf bank_mask:0xf
	v_add_f32_dpp v71, v71, v71 row_mirror row_mask:0xf bank_mask:0xf
	s_and_saveexec_b64 s[94:95], s[10:11]
	s_cbranch_execz .LBB0_386
	ds_write_b128 v102, v[68:71] offset:128
.LBB0_386:
	s_or_b64 exec, exec, s[94:95]
	ds_read_b64 v[2:3], v234 offset:53344
	ds_read_u16 v70, v235 offset:25344
	ds_read_u16 v71, v235 offset:25872
	s_waitcnt lgkmcnt(2)
	v_lshlrev_b32_e32 v68, 16, v2
	s_waitcnt lgkmcnt(1)
	v_lshlrev_b32_e32 v70, 16, v70
	s_waitcnt lgkmcnt(0)
	v_lshlrev_b32_e32 v71, 16, v71
	v_pk_mul_f32 v[76:77], v[70:71], s[96:97] op_sel_hi:[1,0]
	v_and_b32_e32 v69, 0xffff0000, v2
	v_exp_f32_e32 v76, v76
	v_exp_f32_e32 v77, v77
	v_pk_fma_f32 v[68:69], v[154:155], v[68:69], v[80:81]
	v_lshlrev_b32_e32 v2, 16, v3
	v_and_b32_e32 v3, 0xffff0000, v3
	v_pk_add_f32 v[76:77], v[76:77], 1.0 op_sel_hi:[1,0]
	v_pk_fma_f32 v[2:3], v[154:155], v[2:3], v[82:83]
	v_rcp_f32_e32 v76, v76
	v_rcp_f32_e32 v77, v77
	s_nop 0
	v_pk_mul_f32 v[70:71], v[76:77], v[70:71]
	s_nop 0
	v_pk_mul_f32 v[68:69], v[68:69], v[70:71]
	s_nop 0
	v_cvt_pk_bf16_f32 v76, v68, v69
	ds_write_b16 v235, v76 offset:25344
	ds_write_b16_d16_hi v235, v76 offset:25872
	ds_read_u16 v68, v235 offset:26400
	ds_read_u16 v69, v235 offset:26928
	s_waitcnt lgkmcnt(1)
	v_lshlrev_b32_e32 v68, 16, v68
	s_waitcnt lgkmcnt(0)
	v_lshlrev_b32_e32 v69, 16, v69
	v_pk_mul_f32 v[70:71], v[68:69], s[96:97] op_sel_hi:[1,0]
	s_nop 0
	v_exp_f32_e32 v70, v70
	v_exp_f32_e32 v71, v71
	s_nop 0
	v_pk_add_f32 v[70:71], v[70:71], 1.0 op_sel_hi:[1,0]
	s_nop 0
	v_rcp_f32_e32 v70, v70
	v_rcp_f32_e32 v71, v71
	s_nop 0
	v_pk_mul_f32 v[68:69], v[70:71], v[68:69]
	s_nop 0
	v_pk_mul_f32 v[2:3], v[2:3], v[68:69]
	s_nop 0
	v_cvt_pk_bf16_f32 v77, v2, v3
	ds_write_b16 v235, v77 offset:26400
	ds_write_b16_d16_hi v235, v77 offset:26928
	ds_read_b64 v[2:3], v234 offset:55648
	ds_read_u16 v70, v235 offset:25376
	ds_read_u16 v71, v235 offset:25904
	s_waitcnt lgkmcnt(2)
	v_lshlrev_b32_e32 v68, 16, v2
	v_and_b32_e32 v69, 0xffff0000, v2
	s_waitcnt lgkmcnt(1)
	v_lshlrev_b32_e32 v70, 16, v70
	s_waitcnt lgkmcnt(0)
	v_lshlrev_b32_e32 v71, 16, v71
	v_pk_fma_f32 v[68:69], v[154:155], v[68:69], v[72:73]
	v_pk_mul_f32 v[72:73], v[70:71], s[96:97] op_sel_hi:[1,0]
	v_lshlrev_b32_e32 v2, 16, v3
	v_exp_f32_e32 v72, v72
	v_exp_f32_e32 v73, v73
	v_and_b32_e32 v3, 0xffff0000, v3
	v_pk_fma_f32 v[2:3], v[154:155], v[2:3], v[74:75]
	v_pk_add_f32 v[72:73], v[72:73], 1.0 op_sel_hi:[1,0]
	s_nop 0
	v_rcp_f32_e32 v72, v72
	v_rcp_f32_e32 v73, v73
	s_nop 0
	v_pk_mul_f32 v[70:71], v[72:73], v[70:71]
	s_nop 0
	v_pk_mul_f32 v[68:69], v[68:69], v[70:71]
	s_nop 0
	v_cvt_pk_bf16_f32 v72, v68, v69
	ds_write_b16 v235, v72 offset:25376
	ds_write_b16_d16_hi v235, v72 offset:25904
	ds_read_u16 v68, v235 offset:26432
	ds_read_u16 v69, v235 offset:26960
	s_waitcnt lgkmcnt(1)
	v_lshlrev_b32_e32 v68, 16, v68
	s_waitcnt lgkmcnt(0)
	v_lshlrev_b32_e32 v69, 16, v69
	v_pk_mul_f32 v[70:71], v[68:69], s[96:97] op_sel_hi:[1,0]
	s_nop 0
	v_exp_f32_e32 v70, v70
	v_exp_f32_e32 v71, v71
	s_nop 0
	v_pk_add_f32 v[70:71], v[70:71], 1.0 op_sel_hi:[1,0]
	s_nop 0
	v_rcp_f32_e32 v70, v70
	v_rcp_f32_e32 v71, v71
	s_nop 0
	v_pk_mul_f32 v[68:69], v[70:71], v[68:69]
	s_nop 0
	v_pk_mul_f32 v[2:3], v[2:3], v[68:69]
	v_lshlrev_b32_e32 v68, 16, v72
	v_cvt_pk_bf16_f32 v73, v2, v3
	ds_write_b16 v235, v73 offset:26432
	ds_write_b16_d16_hi v235, v73 offset:26960
	v_and_b32_e32 v69, 0xffff0000, v72
	v_lshlrev_b32_e32 v72, 16, v73
	v_and_b32_e32 v73, 0xffff0000, v73
	v_lshlrev_b32_e32 v2, 16, v76
	v_and_b32_e32 v3, 0xffff0000, v76
	v_pk_mul_f32 v[68:69], v[68:69], v[68:69]
	v_lshlrev_b32_e32 v70, 16, v77
	v_and_b32_e32 v71, 0xffff0000, v77
	v_pk_mul_f32 v[72:73], v[72:73], v[72:73]
	v_pk_fma_f32 v[2:3], v[2:3], v[2:3], v[68:69]
	v_pk_fma_f32 v[70:71], v[70:71], v[70:71], v[72:73]
	s_nop 0
	v_add_f32_dpp v2, v2, v2 quad_perm:[1,0,3,2] row_mask:0xf bank_mask:0xf
	v_add_f32_dpp v3, v3, v3 quad_perm:[1,0,3,2] row_mask:0xf bank_mask:0xf
	v_add_f32_dpp v70, v70, v70 quad_perm:[1,0,3,2] row_mask:0xf bank_mask:0xf
	v_add_f32_dpp v71, v71, v71 quad_perm:[1,0,3,2] row_mask:0xf bank_mask:0xf
	v_add_f32_dpp v2, v2, v2 quad_perm:[2,3,0,1] row_mask:0xf bank_mask:0xf
	v_add_f32_dpp v3, v3, v3 quad_perm:[2,3,0,1] row_mask:0xf bank_mask:0xf
	v_add_f32_dpp v70, v70, v70 quad_perm:[2,3,0,1] row_mask:0xf bank_mask:0xf
	v_add_f32_dpp v71, v71, v71 quad_perm:[2,3,0,1] row_mask:0xf bank_mask:0xf
	v_add_f32_dpp v2, v2, v2 row_half_mirror row_mask:0xf bank_mask:0xf
	v_add_f32_dpp v3, v3, v3 row_half_mirror row_mask:0xf bank_mask:0xf
	v_add_f32_dpp v70, v70, v70 row_half_mirror row_mask:0xf bank_mask:0xf
	v_add_f32_dpp v71, v71, v71 row_half_mirror row_mask:0xf bank_mask:0xf
	v_add_f32_dpp v68, v2, v2 row_mirror row_mask:0xf bank_mask:0xf
	v_add_f32_dpp v69, v3, v3 row_mirror row_mask:0xf bank_mask:0xf
	v_add_f32_dpp v70, v70, v70 row_mirror row_mask:0xf bank_mask:0xf
	v_add_f32_dpp v71, v71, v71 row_mirror row_mask:0xf bank_mask:0xf
	s_and_saveexec_b64 s[94:95], s[10:11]
	s_cbranch_execz .LBB0_388
	ds_write_b128 v102, v[68:71] offset:192
